# seams 3 (WOA->UP0) and 10 (WOB->UP1) become panel-group seams with arrival-counter waits on the groups whose live buffers the next output overlays; overlay-protecting L2 write-backs are per group afte
# speedup vs baseline: 1.0093x; 1.0093x over previous
.LBB0_768:
	v_readlane_b32 s0, v249, 4
	v_readlane_b32 s1, v249, 5
	s_cmp_lt_i32 s1, 5
	s_mov_b64 s[0:1], -1
	s_cbranch_scc0 .LBB0_770
	s_waitcnt vmcnt(0) lgkmcnt(0)
	s_barrier
	s_mov_b64 s[0:1], 0
.LBB0_770:
	s_andn2_b64 vcc, exec, s[0:1]
	s_cbranch_vccnz .LBB0_837
	v_readlane_b32 s0, v249, 4
	v_readlane_b32 s1, v249, 5
	s_cmpk_lt_u32 s1, 0x3e9
	s_mov_b64 s[0:1], -1
	s_cbranch_scc0 .LBB0_825
	v_readlane_b32 s2, v249, 2
	s_cmpk_eq_i32 s2, 0x100
	s_cbranch_scc0 .Lg3_xcd
	s_waitcnt vmcnt(0)
	s_waitcnt vmcnt(0) lgkmcnt(0)
	s_barrier
	s_mov_b64 s[0:1], exec
	v_readlane_b32 s2, v249, 10
	v_readlane_b32 s3, v249, 11
	s_and_b64 s[2:3], s[0:1], s[2:3]
	s_mov_b64 exec, s[2:3]
	s_cbranch_execz .Lg3_BB0_1004
	s_lshl_b32 s2, s81, 8
	s_and_b32 s2, s2, 0x3f00
	s_mov_b64 s[4:5], exec
	s_add_u32 s2, s82, s2
	s_addc_u32 s3, s83, 0
	v_readlane_b32 s98, v250, 0
	s_cmp_lg_u32 s98, 0
	s_cbranch_scc1 .Lg3_skip_wbl2_2
	buffer_wbl2 sc1

.LBB0_1817:
	s_add_u32 s98, s42, 0xfffc0000
	s_addc_u32 s99, s43, -1
	s_mov_b32 m0, s60
	s_nop 0
	global_load_lds_dwordx4 v138, s[98:99]
	v_add_u32_e32 v154, s64, v156
	ds_read_b128 v[130:133], v154
	ds_read_b128 v[150:153], v154 offset:1024
	ds_read_b128 v[160:163], v154 offset:2048
	ds_read_b128 v[164:167], v154 offset:3072
	v_add_u32_e32 v154, s65, v156
	ds_read_b128 v[168:171], v154
	ds_read_b128 v[172:175], v154 offset:1024
	ds_read_b128 v[180:183], v154 offset:2048
	ds_read_b128 v[184:187], v154 offset:3072
	s_add_u32 s44, s42, 0xfffc0080
	s_addc_u32 s45, s43, -1
	s_cmp_eq_u32 s70, 12
	s_cselect_b32 s47, s35, s45
	s_cselect_b32 s46, s41, s44
	s_cselect_b32 s45, s31, s69
	s_cselect_b32 s44, s67, s68
	v_lshl_add_u64 v[154:155], s[42:43], 0, v[144:145]
	s_add_i32 m0, s53, 0xc000
	ds_read_b128 v[188:191], v158
	ds_read_b128 v[192:195], v158 offset:1024
	ds_read_b128 v[196:199], v158 offset:2048
	ds_read_b128 v[200:203], v158 offset:3072
	ds_read_b128 v[204:207], v158 offset:4096
	ds_read_b128 v[208:211], v158 offset:5120
	ds_read_b128 v[212:215], v158 offset:6144
	ds_read_b128 v[216:219], v158 offset:7168
	global_load_lds_dwordx4 v[154:155], off
	v_lshl_add_u64 v[154:155], s[42:43], 0, v[142:143]
	s_add_i32 m0, s53, 0xe000
	s_nop 0
	global_load_lds_dwordx4 v[154:155], off
	s_waitcnt vmcnt(8)
	s_waitcnt lgkmcnt(0)
	v_mfma_f32_16x16x32_bf16 v[114:117], v[130:133], v[188:191], v[114:117]
	v_mfma_f32_16x16x32_bf16 v[118:121], v[160:163], v[188:191], v[118:121]
	v_mfma_f32_16x16x32_bf16 v[98:101], v[130:133], v[196:199], v[98:101]
	v_mfma_f32_16x16x32_bf16 v[102:105], v[160:163], v[196:199], v[102:105]
	s_barrier
	s_setprio 1
	v_mfma_f32_16x16x32_bf16 v[82:85], v[130:133], v[204:207], v[82:85]
	v_mfma_f32_16x16x32_bf16 v[86:89], v[160:163], v[204:207], v[86:89]
	v_mfma_f32_16x16x32_bf16 v[66:69], v[130:133], v[212:215], v[66:69]
	v_mfma_f32_16x16x32_bf16 v[70:73], v[160:163], v[212:215], v[70:73]
	v_mfma_f32_16x16x32_bf16 v[114:117], v[150:153], v[192:195], v[114:117]
	v_mfma_f32_16x16x32_bf16 v[118:121], v[164:167], v[192:195], v[118:121]
	v_mfma_f32_16x16x32_bf16 v[98:101], v[150:153], v[200:203], v[98:101]
	v_mfma_f32_16x16x32_bf16 v[102:105], v[164:167], v[200:203], v[102:105]
	v_mfma_f32_16x16x32_bf16 v[82:85], v[150:153], v[208:211], v[82:85]
	v_mfma_f32_16x16x32_bf16 v[86:89], v[164:167], v[208:211], v[86:89]
	v_mfma_f32_16x16x32_bf16 v[66:69], v[150:153], v[216:219], v[66:69]
	v_mfma_f32_16x16x32_bf16 v[70:73], v[164:167], v[216:219], v[70:73]
	v_mfma_f32_16x16x32_bf16 v[122:125], v[168:171], v[188:191], v[122:125]
	v_mfma_f32_16x16x32_bf16 v[126:129], v[180:183], v[188:191], v[126:129]
	v_mfma_f32_16x16x32_bf16 v[106:109], v[168:171], v[196:199], v[106:109]
	v_mfma_f32_16x16x32_bf16 v[110:113], v[180:183], v[196:199], v[110:113]
	v_mfma_f32_16x16x32_bf16 v[90:93], v[168:171], v[204:207], v[90:93]
	v_mfma_f32_16x16x32_bf16 v[94:97], v[180:183], v[204:207], v[94:97]
	v_mfma_f32_16x16x32_bf16 v[74:77], v[168:171], v[212:215], v[74:77]
	v_mfma_f32_16x16x32_bf16 v[78:81], v[180:183], v[212:215], v[78:81]
	v_mfma_f32_16x16x32_bf16 v[122:125], v[172:175], v[192:195], v[122:125]
	v_mfma_f32_16x16x32_bf16 v[126:129], v[184:187], v[192:195], v[126:129]
	v_mfma_f32_16x16x32_bf16 v[106:109], v[172:175], v[200:203], v[106:109]
	v_mfma_f32_16x16x32_bf16 v[110:113], v[184:187], v[200:203], v[110:113]
	v_mfma_f32_16x16x32_bf16 v[90:93], v[172:175], v[208:211], v[90:93]
	v_mfma_f32_16x16x32_bf16 v[94:97], v[184:187], v[208:211], v[94:97]
	v_mfma_f32_16x16x32_bf16 v[74:77], v[172:175], v[216:219], v[74:77]
	v_mfma_f32_16x16x32_bf16 v[78:81], v[184:187], v[216:219], v[78:81]
	s_setprio 0
	s_barrier
	s_add_i32 s71, s64, s52
	v_lshl_add_u64 v[154:155], s[44:45], 0, v[136:137]
	s_mov_b32 m0, s71
	ds_read_b128 v[188:191], v158 offset:16384
	ds_read_b128 v[192:195], v158 offset:17408
	ds_read_b128 v[196:199], v158 offset:18432
	ds_read_b128 v[200:203], v158 offset:19456
	ds_read_b128 v[204:207], v158 offset:20480
	ds_read_b128 v[208:211], v158 offset:21504
	ds_read_b128 v[212:215], v158 offset:22528
	ds_read_b128 v[216:219], v158 offset:23552
	global_load_lds_dwordx4 v[154:155], off
	s_add_i32 m0, s71, 0x2000
	s_add_u32 s72, s44, 0x40000
	v_lshl_add_u64 v[176:177], s[44:45], 0, v[140:141]
	s_addc_u32 s73, s45, 0
	s_add_i32 s71, s65, s52
	global_load_lds_dwordx4 v[176:177], off
	v_lshl_add_u64 v[220:221], s[72:73], 0, v[136:137]
	s_mov_b32 m0, s71
	v_lshl_add_u64 v[222:223], s[46:47], 0, v[138:139]
	global_load_lds_dwordx4 v[220:221], off
	v_lshl_add_u64 v[220:221], s[72:73], 0, v[140:141]
	s_add_i32 m0, s71, 0x2000
	s_nop 0
	global_load_lds_dwordx4 v[220:221], off
	v_lshl_add_u64 v[220:221], s[46:47], 0, v[134:135]
	s_mov_b32 m0, s53
	s_nop 0
	global_load_lds_dwordx4 v[220:221], off
	s_waitcnt vmcnt(7)
	s_waitcnt lgkmcnt(0)
	v_mfma_f32_16x16x32_bf16 v[50:53], v[130:133], v[188:191], v[50:53]
	v_mfma_f32_16x16x32_bf16 v[54:57], v[160:163], v[188:191], v[54:57]
	v_mfma_f32_16x16x32_bf16 v[26:29], v[130:133], v[196:199], v[26:29]
	v_mfma_f32_16x16x32_bf16 v[30:33], v[160:163], v[196:199], v[30:33]
	s_barrier
	s_setprio 1
	v_mfma_f32_16x16x32_bf16 v[18:21], v[130:133], v[204:207], v[18:21]
	v_mfma_f32_16x16x32_bf16 v[22:25], v[160:163], v[204:207], v[22:25]
	v_mfma_f32_16x16x32_bf16 v[2:5], v[130:133], v[212:215], v[2:5]
	v_mfma_f32_16x16x32_bf16 v[6:9], v[160:163], v[212:215], v[6:9]
	v_mfma_f32_16x16x32_bf16 v[50:53], v[150:153], v[192:195], v[50:53]
	v_mfma_f32_16x16x32_bf16 v[54:57], v[164:167], v[192:195], v[54:57]
	v_mfma_f32_16x16x32_bf16 v[26:29], v[150:153], v[200:203], v[26:29]
	v_mfma_f32_16x16x32_bf16 v[30:33], v[164:167], v[200:203], v[30:33]
	v_mfma_f32_16x16x32_bf16 v[18:21], v[150:153], v[208:211], v[18:21]
	v_mfma_f32_16x16x32_bf16 v[22:25], v[164:167], v[208:211], v[22:25]
	v_mfma_f32_16x16x32_bf16 v[2:5], v[150:153], v[216:219], v[2:5]
	v_mfma_f32_16x16x32_bf16 v[6:9], v[164:167], v[216:219], v[6:9]
	v_mfma_f32_16x16x32_bf16 v[58:61], v[168:171], v[188:191], v[58:61]
	v_mfma_f32_16x16x32_bf16 v[62:65], v[180:183], v[188:191], v[62:65]
	v_mfma_f32_16x16x32_bf16 v[42:45], v[168:171], v[196:199], v[42:45]
	v_mfma_f32_16x16x32_bf16 v[46:49], v[180:183], v[196:199], v[46:49]
	v_mfma_f32_16x16x32_bf16 v[34:37], v[168:171], v[204:207], v[34:37]
	v_mfma_f32_16x16x32_bf16 v[38:41], v[180:183], v[204:207], v[38:41]
	v_mfma_f32_16x16x32_bf16 v[10:13], v[168:171], v[212:215], v[10:13]
	v_mfma_f32_16x16x32_bf16 v[14:17], v[180:183], v[212:215], v[14:17]
	v_mfma_f32_16x16x32_bf16 v[58:61], v[172:175], v[192:195], v[58:61]
	v_mfma_f32_16x16x32_bf16 v[62:65], v[184:187], v[192:195], v[62:65]
	v_mfma_f32_16x16x32_bf16 v[42:45], v[172:175], v[200:203], v[42:45]
	v_mfma_f32_16x16x32_bf16 v[46:49], v[184:187], v[200:203], v[46:49]
	v_mfma_f32_16x16x32_bf16 v[34:37], v[172:175], v[208:211], v[34:37]
	v_mfma_f32_16x16x32_bf16 v[38:41], v[184:187], v[208:211], v[38:41]
	v_mfma_f32_16x16x32_bf16 v[10:13], v[172:175], v[216:219], v[10:13]
	v_mfma_f32_16x16x32_bf16 v[14:17], v[184:187], v[216:219], v[14:17]
	s_setprio 0
	s_barrier
	s_mov_b32 m0, s54
	s_nop 0
	global_load_lds_dwordx4 v138, s[46:47]
	s_add_i32 s71, 0, 0x18000
	s_add_i32 s72, 0, 0x1c000
	v_add_u32_e32 v164, s71, v156
	v_add_u32_e32 v179, s72, v156
	ds_read_b128 v[130:133], v164
	ds_read_b128 v[150:153], v164 offset:1024
	ds_read_b128 v[160:163], v164 offset:2048
	ds_read_b128 v[164:167], v164 offset:3072
	ds_read_b128 v[168:171], v179
	ds_read_b128 v[172:175], v179 offset:1024
	ds_read_b128 v[180:183], v179 offset:2048
	ds_read_b128 v[184:187], v179 offset:3072
	s_add_u32 s46, s46, 0x40000
	s_addc_u32 s47, s47, 0
	s_mov_b32 m0, s55
	v_lshl_add_u64 v[224:225], s[46:47], 0, v[134:135]
	ds_read_b128 v[188:191], v158 offset:32768
	ds_read_b128 v[192:195], v158 offset:33792
	ds_read_b128 v[196:199], v158 offset:34816
	ds_read_b128 v[200:203], v158 offset:35840
	ds_read_b128 v[204:207], v158 offset:36864
	ds_read_b128 v[208:211], v158 offset:37888
	ds_read_b128 v[212:215], v158 offset:38912
	ds_read_b128 v[216:219], v158 offset:39936
	global_load_lds_dwordx4 v[224:225], off
	v_lshl_add_u64 v[224:225], s[46:47], 0, v[138:139]
	s_mov_b32 m0, s56
	s_nop 0
	global_load_lds_dwordx4 v[224:225], off
	s_waitcnt vmcnt(8)
	s_waitcnt lgkmcnt(0)
	v_mfma_f32_16x16x32_bf16 v[114:117], v[130:133], v[188:191], v[114:117]
	v_mfma_f32_16x16x32_bf16 v[118:121], v[160:163], v[188:191], v[118:121]
	v_mfma_f32_16x16x32_bf16 v[98:101], v[130:133], v[196:199], v[98:101]
	v_mfma_f32_16x16x32_bf16 v[102:105], v[160:163], v[196:199], v[102:105]
	s_barrier
	s_setprio 1
	v_mfma_f32_16x16x32_bf16 v[82:85], v[130:133], v[204:207], v[82:85]
	v_mfma_f32_16x16x32_bf16 v[86:89], v[160:163], v[204:207], v[86:89]
	v_mfma_f32_16x16x32_bf16 v[66:69], v[130:133], v[212:215], v[66:69]
	v_mfma_f32_16x16x32_bf16 v[70:73], v[160:163], v[212:215], v[70:73]
	v_mfma_f32_16x16x32_bf16 v[114:117], v[150:153], v[192:195], v[114:117]
	v_mfma_f32_16x16x32_bf16 v[118:121], v[164:167], v[192:195], v[118:121]
	v_mfma_f32_16x16x32_bf16 v[98:101], v[150:153], v[200:203], v[98:101]
	v_mfma_f32_16x16x32_bf16 v[102:105], v[164:167], v[200:203], v[102:105]
	v_mfma_f32_16x16x32_bf16 v[82:85], v[150:153], v[208:211], v[82:85]
	v_mfma_f32_16x16x32_bf16 v[86:89], v[164:167], v[208:211], v[86:89]
	v_mfma_f32_16x16x32_bf16 v[66:69], v[150:153], v[216:219], v[66:69]
	v_mfma_f32_16x16x32_bf16 v[70:73], v[164:167], v[216:219], v[70:73]
	v_mfma_f32_16x16x32_bf16 v[122:125], v[168:171], v[188:191], v[122:125]
	v_mfma_f32_16x16x32_bf16 v[126:129], v[180:183], v[188:191], v[126:129]
	v_mfma_f32_16x16x32_bf16 v[106:109], v[168:171], v[196:199], v[106:109]
	v_mfma_f32_16x16x32_bf16 v[110:113], v[180:183], v[196:199], v[110:113]
	v_mfma_f32_16x16x32_bf16 v[90:93], v[168:171], v[204:207], v[90:93]
	v_mfma_f32_16x16x32_bf16 v[94:97], v[180:183], v[204:207], v[94:97]
	v_mfma_f32_16x16x32_bf16 v[74:77], v[168:171], v[212:215], v[74:77]
	v_mfma_f32_16x16x32_bf16 v[78:81], v[180:183], v[212:215], v[78:81]
	v_mfma_f32_16x16x32_bf16 v[122:125], v[172:175], v[192:195], v[122:125]
	v_mfma_f32_16x16x32_bf16 v[126:129], v[184:187], v[192:195], v[126:129]
	v_mfma_f32_16x16x32_bf16 v[106:109], v[172:175], v[200:203], v[106:109]
	v_mfma_f32_16x16x32_bf16 v[110:113], v[184:187], v[200:203], v[110:113]
	v_mfma_f32_16x16x32_bf16 v[90:93], v[172:175], v[208:211], v[90:93]
	v_mfma_f32_16x16x32_bf16 v[94:97], v[184:187], v[208:211], v[94:97]
	v_mfma_f32_16x16x32_bf16 v[74:77], v[172:175], v[216:219], v[74:77]
	v_mfma_f32_16x16x32_bf16 v[78:81], v[184:187], v[216:219], v[78:81]
	s_setprio 0
	s_barrier
	s_add_i32 s46, s71, s52
	v_lshl_add_u64 v[154:155], v[154:155], 0, s[24:25]
	s_mov_b32 m0, s46
	ds_read_b128 v[188:191], v158 offset:49152
	ds_read_b128 v[192:195], v158 offset:50176
	ds_read_b128 v[196:199], v158 offset:51200
	ds_read_b128 v[200:203], v158 offset:52224
	ds_read_b128 v[204:207], v158 offset:53248
	ds_read_b128 v[208:211], v158 offset:54272
	ds_read_b128 v[212:215], v158 offset:55296
	ds_read_b128 v[216:219], v158 offset:56320
	global_load_lds_dwordx4 v[154:155], off
	s_add_i32 m0, s46, 0x2000
	s_add_u32 s44, s44, 0x40080
	v_lshl_add_u64 v[154:155], v[176:177], 0, s[24:25]
	s_addc_u32 s45, s45, 0
	s_add_i32 s46, s72, s52
	global_load_lds_dwordx4 v[154:155], off
	v_lshl_add_u64 v[154:155], s[44:45], 0, v[136:137]
	s_mov_b32 m0, s46
	s_nop 0
	global_load_lds_dwordx4 v[154:155], off
	v_lshl_add_u64 v[154:155], s[44:45], 0, v[140:141]
	s_add_i32 m0, s46, 0x2000
	s_nop 0
	global_load_lds_dwordx4 v[154:155], off
	v_lshl_add_u64 v[154:155], v[220:221], 0, s[24:25]
	s_mov_b32 m0, s59
	s_nop 0
	global_load_lds_dwordx4 v[154:155], off
	s_waitcnt vmcnt(7)
	s_waitcnt lgkmcnt(0)
	v_mfma_f32_16x16x32_bf16 v[50:53], v[130:133], v[188:191], v[50:53]
	v_mfma_f32_16x16x32_bf16 v[54:57], v[160:163], v[188:191], v[54:57]
	v_mfma_f32_16x16x32_bf16 v[26:29], v[130:133], v[196:199], v[26:29]
	v_mfma_f32_16x16x32_bf16 v[30:33], v[160:163], v[196:199], v[30:33]
	s_barrier
	s_setprio 1
	v_mfma_f32_16x16x32_bf16 v[18:21], v[130:133], v[204:207], v[18:21]
	v_mfma_f32_16x16x32_bf16 v[22:25], v[160:163], v[204:207], v[22:25]
	v_mfma_f32_16x16x32_bf16 v[2:5], v[130:133], v[212:215], v[2:5]
	v_mfma_f32_16x16x32_bf16 v[6:9], v[160:163], v[212:215], v[6:9]
	v_mfma_f32_16x16x32_bf16 v[50:53], v[150:153], v[192:195], v[50:53]
	v_mfma_f32_16x16x32_bf16 v[54:57], v[164:167], v[192:195], v[54:57]
	v_mfma_f32_16x16x32_bf16 v[26:29], v[150:153], v[200:203], v[26:29]
	v_mfma_f32_16x16x32_bf16 v[30:33], v[164:167], v[200:203], v[30:33]
	v_mfma_f32_16x16x32_bf16 v[18:21], v[150:153], v[208:211], v[18:21]
	v_mfma_f32_16x16x32_bf16 v[22:25], v[164:167], v[208:211], v[22:25]
	v_mfma_f32_16x16x32_bf16 v[2:5], v[150:153], v[216:219], v[2:5]
	v_mfma_f32_16x16x32_bf16 v[6:9], v[164:167], v[216:219], v[6:9]
	v_mfma_f32_16x16x32_bf16 v[58:61], v[168:171], v[188:191], v[58:61]
	v_mfma_f32_16x16x32_bf16 v[62:65], v[180:183], v[188:191], v[62:65]
	v_mfma_f32_16x16x32_bf16 v[42:45], v[168:171], v[196:199], v[42:45]
	v_mfma_f32_16x16x32_bf16 v[46:49], v[180:183], v[196:199], v[46:49]
	v_mfma_f32_16x16x32_bf16 v[34:37], v[168:171], v[204:207], v[34:37]
	v_mfma_f32_16x16x32_bf16 v[38:41], v[180:183], v[204:207], v[38:41]
	v_mfma_f32_16x16x32_bf16 v[10:13], v[168:171], v[212:215], v[10:13]
	v_mfma_f32_16x16x32_bf16 v[14:17], v[180:183], v[212:215], v[14:17]
	v_mfma_f32_16x16x32_bf16 v[58:61], v[172:175], v[192:195], v[58:61]
	v_mfma_f32_16x16x32_bf16 v[62:65], v[184:187], v[192:195], v[62:65]
	v_mfma_f32_16x16x32_bf16 v[42:45], v[172:175], v[200:203], v[42:45]
	v_mfma_f32_16x16x32_bf16 v[46:49], v[184:187], v[200:203], v[46:49]
	v_mfma_f32_16x16x32_bf16 v[34:37], v[172:175], v[208:211], v[34:37]
	v_mfma_f32_16x16x32_bf16 v[38:41], v[184:187], v[208:211], v[38:41]
	v_mfma_f32_16x16x32_bf16 v[10:13], v[172:175], v[216:219], v[10:13]
	v_mfma_f32_16x16x32_bf16 v[14:17], v[184:187], v[216:219], v[14:17]
	s_setprio 0
	s_barrier
	s_add_i32 s70, s70, 2
	s_add_u32 s68, s68, 0x100
	s_addc_u32 s69, s69, 0
	s_add_u32 s42, s42, 0x100
	s_addc_u32 s43, s43, 0
	s_cmp_gt_u32 s70, 13
	s_cbranch_scc0 .LBB0_1817
	v_readfirstlane_b32 s98, v178
	s_cmp_lt_u32 s98, 64
	s_cbranch_scc0 .Lkf_b
	v_readlane_b32 s98, v250, 1
	s_cmp_lg_u32 s98, 0
	s_cselect_b32 s98, 1, 0
	s_lshr_b32 s99, s81, 6
	s_cmp_lg_u32 s99, 0
	s_cselect_b32 s99, 1, 0
	s_and_b32 s98, s98, s99
	s_cbranch_scc1 .Lkf_b
	buffer_wbl2 sc1

.LBB0_1904:
	v_readlane_b32 s0, v249, 4
	v_readlane_b32 s1, v249, 5
	s_cmp_lt_i32 s1, 12
	s_mov_b64 s[0:1], -1
	s_cbranch_scc0 .LBB0_1906
	s_waitcnt vmcnt(0) lgkmcnt(0)
	s_barrier
	s_mov_b64 s[0:1], 0
.LBB0_1906:
	s_andn2_b64 vcc, exec, s[0:1]
	s_cbranch_vccnz .LBB0_1973
	v_readlane_b32 s0, v249, 4
	v_readlane_b32 s1, v249, 5
	s_cmpk_lt_u32 s1, 0x3e9
	s_mov_b64 s[0:1], -1
	s_cbranch_scc0 .LBB0_1961
	v_readlane_b32 s2, v249, 2
	s_cmpk_eq_i32 s2, 0x100
	s_cbranch_scc0 .Lg10_xcd
	s_waitcnt vmcnt(0)
	s_waitcnt vmcnt(0) lgkmcnt(0)
	s_barrier
	s_mov_b64 s[0:1], exec
	v_readlane_b32 s2, v249, 10
	v_readlane_b32 s3, v249, 11
	s_and_b64 s[2:3], s[0:1], s[2:3]
	s_mov_b64 exec, s[2:3]
	s_cbranch_execz .Lg10_BB0_1004
	s_lshl_b32 s2, s81, 8
	s_and_b32 s2, s2, 0x3f00
	s_mov_b64 s[4:5], exec
	s_add_u32 s2, s82, s2
	s_addc_u32 s3, s83, 0
	v_readlane_b32 s98, v250, 0
	s_cmp_lg_u32 s98, 0
	s_cbranch_scc1 .Lg10_skip_wbl2_2
	buffer_wbl2 sc1
